# on top of v60: GEMM phases start staggered by blockIdx%8 (XCD slot) x ~0.25us before the first staging loads, smoothing the post-barrier memory burst
# speedup vs baseline: 1.0008x; 1.0008x over previous
.LBB0_212:
	s_andn2_b64 vcc, exec, s[0:1]
	s_cbranch_vccnz .LBB0_276
	s_and_b32 s100, s96, 7
	s_cmp_eq_u32 s100, 0
	s_cbranch_scc1 .Lxstag_done_r
.Lxstag_loop_r:
	s_sleep 8
	s_sub_u32 s100, s100, 1
	s_cmp_lg_u32 s100, 0
	s_cbranch_scc1 .Lxstag_loop_r
.Lxstag_done_r:
	v_ashrrev_i32_e32 v2, 31, v196
	v_lshrrev_b32_e32 v2, 26, v2
	v_add_u32_e32 v2, v196, v2
	v_ashrrev_i32_e32 v6, 6, v2
	v_bfe_i32 v2, v196, 27, 1
	v_lshlrev_b32_e32 v1, 4, v196
	v_lshrrev_b32_e32 v2, 22, v2
	v_add_u32_e32 v2, v1, v2
	v_and_b32_e32 v2, 0xfffffc00, v2
	v_sub_u32_e32 v2, v1, v2
	v_lshrrev_b32_e32 v3, 4, v2
	v_bitop3_b32 v2, v3, v2, 32 bitop3:0x6c
	v_ashrrev_i32_e32 v4, 31, v2
	v_lshrrev_b32_e32 v4, 26, v4
	v_add_u32_e32 v4, v2, v4
	v_writelane_b32 v255, s83, 59
	s_and_b64 s[0:1], s[4:5], exec
	v_lshlrev_b32_e32 v3, 3, v6
	v_ashrrev_i32_e32 v7, 6, v4
	v_and_b32_e32 v4, 0xc0, v4
	v_writelane_b32 v255, s72, 58
	s_mov_b32 s0, 0x3500000
	v_and_b32_e32 v3, -16, v3
	v_sub_u32_e32 v2, v2, v4
	s_cselect_b32 s0, s0, 0x2d00000
	v_readlane_b32 s6, v255, 50
	v_add_u32_e32 v3, v7, v3
	v_ashrrev_i16_sdwa v2, v226, sext(v2) dst_sel:DWORD dst_unused:UNUSED_PAD src0_sel:DWORD src1_sel:BYTE_0
	s_cselect_b32 s52, s39, s59
	s_cselect_b32 s53, s38, s58
	s_add_u32 s91, s6, s0
	v_lshlrev_b32_e32 v5, 5, v6
	s_waitcnt lgkmcnt(1)
	v_bfe_i32 v8, v2, 0, 16
	v_lshlrev_b32_e32 v2, 1, v3
	v_lshrrev_b32_e32 v4, 2, v3
	v_and_b32_e32 v9, 3, v7
	s_mov_b32 s0, 0x1fffe0
	v_and_b32_e32 v5, 32, v5
	v_and_b32_e32 v2, 24, v2
	v_and_b32_e32 v4, 4, v4
	v_and_or_b32 v9, v3, s0, v9
	v_or3_b32 v2, v9, v4, v2
	v_add_lshl_u32 v4, v5, v8, 1
	v_add_u32_e32 v1, 0x2000, v1
	v_lshl_add_u32 v164, v2, 11, v4
	v_ashrrev_i32_e32 v2, 31, v1
	v_lshrrev_b32_e32 v2, 22, v2
	v_add_u32_e32 v2, v1, v2
	v_ashrrev_i32_e32 v9, 10, v2
	v_mul_i32_i24_e32 v2, 0x400, v9
	v_sub_u32_e32 v1, v1, v2
	v_lshrrev_b32_e32 v2, 4, v1
	v_bitop3_b32 v1, v2, v1, 32 bitop3:0x6c
	v_lshl_add_u32 v162, v3, 7, v4
	v_ashrrev_i32_e32 v3, 31, v1
	v_lshrrev_b32_e32 v3, 26, v3
	v_lshlrev_b32_e32 v2, 3, v9
	v_add_u32_e32 v3, v1, v3
	v_readlane_b32 s7, v255, 51
	v_and_b32_e32 v2, -16, v2
	s_waitcnt lgkmcnt(0)
	v_ashrrev_i32_e32 v10, 6, v3
	s_addc_u32 s93, s7, 0
	s_ashr_i32 s6, s2, 6
	v_add_u32_e32 v2, v10, v2
	v_and_b32_e32 v3, 0xc0, v3
	v_and_b32_e32 v5, 3, v10
	s_ashr_i32 s9, s8, 31
	s_ashr_i32 s45, s44, 31
	v_sub_u32_e32 v1, v1, v3
	v_and_or_b32 v5, v2, s0, v5
	s_ashr_i32 s7, s2, 8
	s_lshl_b32 s69, s6, 10
	s_lshl_b64 s[0:1], s[8:9], 19
	s_lshl_b64 s[10:11], s[44:45], 19
	v_ashrrev_i16_sdwa v1, v226, sext(v1) dst_sel:DWORD dst_unused:UNUSED_PAD src0_sel:DWORD src1_sel:BYTE_0
	s_add_u32 s10, s91, s10
	v_lshlrev_b32_e32 v4, 5, v9
	v_bfe_i32 v11, v1, 0, 16
	v_lshlrev_b32_e32 v1, 1, v2
	v_lshrrev_b32_e32 v3, 2, v2
	s_addc_u32 s11, s93, s11
	s_add_i32 s45, s69, 0
	v_and_b32_e32 v4, 32, v4
	v_and_b32_e32 v1, 24, v1
	v_and_b32_e32 v3, 4, v3
	s_add_i32 m0, s45, 0x10000
	v_or3_b32 v1, v5, v3, v1
	v_add_lshl_u32 v3, v4, v11, 1
	global_load_lds_dwordx4 v164, s[10:11]
	s_add_i32 m0, s45, 0x12000
	v_lshl_add_u32 v168, v1, 11, v3
	s_add_u32 s12, s10, 0x40000
	global_load_lds_dwordx4 v168, s[10:11]
	s_addc_u32 s13, s11, 0
	s_add_i32 m0, s45, 0x14000
	v_lshl_add_u32 v166, v2, 7, v3
	global_load_lds_dwordx4 v164, s[12:13]
	s_add_i32 m0, s45, 0x16000
	s_add_u32 s42, s53, s0
	s_addc_u32 s43, s52, s1
	s_add_i32 s3, s45, 0x2000
	global_load_lds_dwordx4 v168, s[12:13]
	s_mov_b32 m0, s45
	s_add_u32 s0, s42, 0x4000
	global_load_lds_dwordx4 v162, s[42:43]
	s_mov_b32 m0, s3
	s_addc_u32 s1, s43, 0
	s_add_i32 s31, s45, 0x4000
	global_load_lds_dwordx4 v166, s[42:43]
	s_mov_b32 m0, s31
	s_add_i32 s33, s45, 0x6000
	global_load_lds_dwordx4 v162, s[0:1]
	s_mov_b32 m0, s33
	v_mov_b32_e32 v165, v191
	global_load_lds_dwordx4 v166, s[0:1]
	v_mov_b32_e32 v169, v191
	s_cmp_eq_u32 s7, 1
	v_mov_b32_e32 v253, 0x2000
	v_lshl_add_u64 v[2:3], s[10:11], 0, v[164:165]
	s_cselect_b64 s[0:1], -1, 0
	s_cmp_lg_u32 s7, 1
	v_lshl_add_u64 v[4:5], s[10:11], 0, v[168:169]
	s_cbranch_scc1 .LBB0_215
	s_barrier

.LBB0_293:
	s_and_b32 s100, s96, 7
	s_cmp_eq_u32 s100, 0
	s_cbranch_scc1 .Lxstag_done_s

.Lxstag_done_p:
	v_ashrrev_i32_e32 v2, 31, v196
	v_lshrrev_b32_e32 v2, 26, v2
	v_add_u32_e32 v2, v196, v2
	v_ashrrev_i32_e32 v6, 6, v2
	v_bfe_i32 v2, v196, 27, 1
	v_lshlrev_b32_e32 v1, 4, v196
	v_lshrrev_b32_e32 v2, 22, v2
	v_add_u32_e32 v2, v1, v2
	v_and_b32_e32 v2, 0xfffffc00, v2
	v_sub_u32_e32 v2, v1, v2
	v_lshrrev_b32_e32 v3, 4, v2
	s_and_b64 s[0:1], s[4:5], exec
	v_bitop3_b32 v2, v3, v2, 32 bitop3:0x6c
	s_mov_b32 s0, 0x1c00000
	v_ashrrev_i32_e32 v4, 31, v2
	s_cselect_b32 s10, 0x2d00000, s0
	v_readlane_b32 s0, v255, 49
	v_lshrrev_b32_e32 v4, 26, v4
	s_cmp_lt_u32 s0, 64
	v_add_u32_e32 v4, v2, v4
	s_cselect_b64 s[14:15], -1, 0
	v_lshlrev_b32_e32 v3, 3, v6
	v_ashrrev_i32_e32 v7, 6, v4
	v_and_b32_e32 v4, 0xc0, v4
	s_and_b64 s[0:1], s[14:15], exec
	v_and_b32_e32 v3, -16, v3
	v_sub_u32_e32 v2, v2, v4
	s_cselect_b32 s0, 0xb00000, s10
	v_readlane_b32 s10, v255, 50
	v_add_u32_e32 v3, v7, v3
	v_ashrrev_i16_sdwa v2, v226, sext(v2) dst_sel:DWORD dst_unused:UNUSED_PAD src0_sel:DWORD src1_sel:BYTE_0
	s_add_u32 s13, s10, s0
	v_lshlrev_b32_e32 v5, 5, v6
	s_waitcnt lgkmcnt(1)
	v_bfe_i32 v8, v2, 0, 16
	v_lshlrev_b32_e32 v2, 1, v3
	v_lshrrev_b32_e32 v4, 2, v3
	v_and_b32_e32 v9, 3, v7
	s_mov_b32 s0, 0x1fffe0
	v_and_b32_e32 v5, 32, v5
	v_and_b32_e32 v2, 24, v2
	v_and_b32_e32 v4, 4, v4
	v_and_or_b32 v9, v3, s0, v9
	v_or3_b32 v2, v9, v4, v2
	v_add_lshl_u32 v4, v5, v8, 1
	v_add_u32_e32 v1, 0x2000, v1
	v_lshl_add_u32 v148, v2, 11, v4
	v_ashrrev_i32_e32 v2, 31, v1
	v_lshrrev_b32_e32 v2, 22, v2
	v_add_u32_e32 v2, v1, v2
	v_ashrrev_i32_e32 v9, 10, v2
	v_mul_i32_i24_e32 v2, 0x400, v9
	v_sub_u32_e32 v1, v1, v2
	v_lshrrev_b32_e32 v2, 4, v1
	v_bitop3_b32 v1, v2, v1, 32 bitop3:0x6c
	v_lshl_add_u32 v146, v3, 7, v4
	v_ashrrev_i32_e32 v3, 31, v1
	v_lshrrev_b32_e32 v3, 26, v3
	v_lshlrev_b32_e32 v2, 3, v9
	v_add_u32_e32 v3, v1, v3
	v_readlane_b32 s11, v255, 51
	v_and_b32_e32 v2, -16, v2
	s_waitcnt lgkmcnt(0)
	v_ashrrev_i32_e32 v10, 6, v3
	s_addc_u32 s21, s11, 0
	s_ashr_i32 s16, s9, 6
	v_add_u32_e32 v2, v10, v2
	v_and_b32_e32 v3, 0xc0, v3
	v_and_b32_e32 v5, 3, v10
	s_ashr_i32 s47, s46, 31
	s_ashr_i32 s43, s42, 31
	v_sub_u32_e32 v1, v1, v3
	v_and_or_b32 v5, v2, s0, v5
	s_ashr_i32 s17, s9, 8
	s_lshl_b32 s28, s16, 10
	s_lshl_b64 s[10:11], s[46:47], 19
	s_lshl_b64 s[0:1], s[42:43], 19
	v_ashrrev_i16_sdwa v1, v226, sext(v1) dst_sel:DWORD dst_unused:UNUSED_PAD src0_sel:DWORD src1_sel:BYTE_0
	s_add_u32 s0, s13, s0
	v_lshlrev_b32_e32 v4, 5, v9
	v_bfe_i32 v11, v1, 0, 16
	v_lshlrev_b32_e32 v1, 1, v2
	v_lshrrev_b32_e32 v3, 2, v2
	s_addc_u32 s1, s21, s1
	s_add_i32 s29, s28, 0
	v_and_b32_e32 v4, 32, v4
	v_and_b32_e32 v1, 24, v1
	v_and_b32_e32 v3, 4, v3
	s_add_i32 m0, s29, 0x10000
	v_or3_b32 v1, v5, v3, v1
	v_add_lshl_u32 v3, v4, v11, 1
	global_load_lds_dwordx4 v148, s[0:1]
	s_add_i32 m0, s29, 0x12000
	v_lshl_add_u32 v152, v1, 11, v3
	s_add_u32 s18, s0, 0x40000
	global_load_lds_dwordx4 v152, s[0:1]
	s_addc_u32 s19, s1, 0
	s_add_i32 m0, s29, 0x14000
	v_lshl_add_u32 v150, v2, 7, v3
	global_load_lds_dwordx4 v148, s[18:19]
	s_add_i32 m0, s29, 0x16000
	s_add_u32 s50, s58, s10
	s_addc_u32 s51, s59, s11
	s_add_i32 s31, s29, 0x2000
	global_load_lds_dwordx4 v152, s[18:19]
	s_mov_b32 m0, s29
	s_add_u32 s10, s50, 0x4000
	global_load_lds_dwordx4 v146, s[50:51]
	s_mov_b32 m0, s31
	s_addc_u32 s11, s51, 0
	s_add_i32 s33, s29, 0x4000
	global_load_lds_dwordx4 v150, s[50:51]
	s_mov_b32 m0, s33
	s_add_i32 s36, s29, 0x6000
	global_load_lds_dwordx4 v146, s[10:11]
	s_mov_b32 m0, s36
	v_mov_b32_e32 v149, v191
	global_load_lds_dwordx4 v150, s[10:11]
	v_mov_b32_e32 v153, v191
	s_cmp_eq_u32 s17, 1
	s_mov_b32 s57, s72
	v_lshl_add_u64 v[2:3], s[0:1], 0, v[148:149]
	s_cselect_b64 s[10:11], -1, 0
	s_cmp_lg_u32 s17, 1
	v_lshl_add_u64 v[4:5], s[0:1], 0, v[152:153]
	s_cbranch_scc1 .LBB0_456
	s_barrier

	.amdhsa_kernel _Z14fwd_megakernel6Params
		.amdhsa_group_segment_fixed_size 8192
		.amdhsa_private_segment_fixed_size 0
		.amdhsa_kernarg_size 504
		.amdhsa_user_sgpr_count 2
		.amdhsa_user_sgpr_dispatch_ptr 0
		.amdhsa_user_sgpr_queue_ptr 0
		.amdhsa_user_sgpr_kernarg_segment_ptr 1
		.amdhsa_user_sgpr_dispatch_id 0
		.amdhsa_user_sgpr_kernarg_preload_length 0
		.amdhsa_user_sgpr_kernarg_preload_offset 0
		.amdhsa_user_sgpr_private_segment_size 0
		.amdhsa_uses_dynamic_stack 0
		.amdhsa_enable_private_segment 0
		.amdhsa_system_sgpr_workgroup_id_x 1
		.amdhsa_system_sgpr_workgroup_id_y 0
		.amdhsa_system_sgpr_workgroup_id_z 0
		.amdhsa_system_sgpr_workgroup_info 0
		.amdhsa_system_vgpr_workitem_id 2
		.amdhsa_next_free_vgpr 256
		.amdhsa_next_free_sgpr 102
		.amdhsa_accum_offset 256
		.amdhsa_reserve_vcc 1
		.amdhsa_float_round_mode_32 0
		.amdhsa_float_round_mode_16_64 0
		.amdhsa_float_denorm_mode_32 3
		.amdhsa_float_denorm_mode_16_64 3
		.amdhsa_dx10_clamp 1
		.amdhsa_ieee_mode 1
		.amdhsa_fp16_overflow 0
		.amdhsa_tg_split 0
		.amdhsa_exception_fp_ieee_invalid_op 0
		.amdhsa_exception_fp_denorm_src 0
		.amdhsa_exception_fp_ieee_div_zero 0
		.amdhsa_exception_fp_ieee_overflow 0
		.amdhsa_exception_fp_ieee_underflow 0
		.amdhsa_exception_fp_ieee_inexact 0
		.amdhsa_exception_int_div_zero 0
	.end_amdhsa_kernel

amdhsa.kernels:
  - .agpr_count:     0
    .args:
      - .offset:         0
        .size:           248
        .value_kind:     by_value
      - .offset:         248
        .size:           4
        .value_kind:     hidden_block_count_x
      - .offset:         252
        .size:           4
        .value_kind:     hidden_block_count_y
      - .offset:         256
        .size:           4
        .value_kind:     hidden_block_count_z
      - .offset:         260
        .size:           2
        .value_kind:     hidden_group_size_x
      - .offset:         262
        .size:           2
        .value_kind:     hidden_group_size_y
      - .offset:         264
        .size:           2
        .value_kind:     hidden_group_size_z
      - .offset:         266
        .size:           2
        .value_kind:     hidden_remainder_x
      - .offset:         268
        .size:           2
        .value_kind:     hidden_remainder_y
      - .offset:         270
        .size:           2
        .value_kind:     hidden_remainder_z
      - .offset:         288
        .size:           8
        .value_kind:     hidden_global_offset_x
      - .offset:         296
        .size:           8
        .value_kind:     hidden_global_offset_y
      - .offset:         304
        .size:           8
        .value_kind:     hidden_global_offset_z
      - .offset:         312
        .size:           2
        .value_kind:     hidden_grid_dims
      - .offset:         336
        .size:           8
        .value_kind:     hidden_multigrid_sync_arg
      - .offset:         368
        .size:           4
        .value_kind:     hidden_dynamic_lds_size
    .group_segment_fixed_size: 8192
    .kernarg_segment_align: 8
    .kernarg_segment_size: 504
    .language:       OpenCL C
    .language_version:
      - 2
      - 0
    .max_flat_workgroup_size: 512
    .name:           _Z14fwd_megakernel6Params
    .private_segment_fixed_size: 0
    .sgpr_count:     108
    .sgpr_spill_count: 65
    .symbol:         _Z14fwd_megakernel6Params.kd
    .uniform_work_group_size: 1
    .uses_dynamic_stack: false
    .vgpr_count:     256
    .vgpr_spill_count: 0
    .wavefront_size: 64
